# adds attention gate-tile loads issued at pass start (were loaded and waited in the pass epilogue)
# speedup vs baseline: 1.0045x; 1.0045x over previous
; DEVI unsigned pk2(float lo, float hi) { f32x2 v = {lo, hi}; bf16x2_t b = __builtin_convertvector(v, bf16x2_t); return __builtin_bit_cast(unsigned, b); }
; DEVI float bflo(unsigned u) { return __uint_as_float(u << 16); }
; DEVI float bfhi(unsigned u) { return __uint_as_float(u & 0xffff0000u); }
; DEVI void attn_item(const P& p, int item, char* smem) {
;     ...
; #pragma unroll
;         for (int m = 0; m < 2; ++m) {
;             float l = lrow[m];
;             l = rowsum4(l);
;             const float inv = __builtin_amdgcn_rcpf(l);
;             uint2 og4[4];
; #pragma unroll
;             for (int nd = 0; nd < 4; ++nd) {
;                 const size_t off = (size_t)(mo + 16 * m + fr) * 1024 + 16 * nd + 4 * fq;
;                 const uint2 g = *(const uint2*)(SGT + off);
;                 const f32x4 v = O[nd][m] * inv;
;                 og4[nd].x = pk2(v[0] * bflo(g.x), v[1] * bfhi(g.x)); og4[nd].y = pk2(v[2] * bflo(g.y), v[3] * bfhi(g.y));
;             }
; #pragma unroll
;             for (int nd = 0; nd < 4; nd += 2)
;                 *(uint4*)(OG + (size_t)(mo + 16 * m + fr) * 1024 + 16 * (nd + (fq & 1)) + 8 * (fq >> 1)) = widen16(og4[nd], og4[nd + 1]);
;         }
.LBB0_1431:
	v_or_b32_e32 v0, v122, v125
	v_lshlrev_b32_e32 v0, 1, v0
	s_waitcnt vmcnt(3)
	v_lshl_add_u64 v[22:23], v[110:111], 0, v[0:1]
	s_waitcnt vmcnt(5)
	v_or_b32_e32 v32, v120, v125
	v_lshlrev_b32_e32 v0, 1, v122
	v_lshl_add_u64 v[22:23], v[118:119], 0, v[0:1]
	v_lshlrev_b32_e32 v0, 1, v32
	v_lshl_add_u64 v[32:33], v[110:111], 0, v[0:1]
	v_mov_b32_e32 v50, v139
	s_nop 1
	v_permlane32_swap_b32_e32 v139, v50
	v_add_f32_e32 v52, v139, v50
	v_mov_b32_e32 v0, v158
	s_nop 0
	s_nop 0
	v_permlane32_swap_b32_e32 v158, v0
	v_add_f32_e32 v0, v158, v0
	v_mov_b32_e32 v53, v0
	v_mov_b32_e32 v54, v52
	s_nop 0
	v_permlane16_swap_b32_e32 v0, v53
	v_permlane16_swap_b32_e32 v52, v54
	v_add_f32_e32 v0, v0, v53
	v_add_f32_e32 v52, v52, v54
	v_rcp_f32_e32 v0, v0
	v_rcp_f32_e32 v52, v52
	s_mov_b32 s4, 32
	s_mov_b64 s[2:3], 0
	v_pk_mul_f32 v[40:41], v[40:41], v[0:1] op_sel_hi:[1,0]
	v_pk_mul_f32 v[38:39], v[38:39], v[0:1] op_sel_hi:[1,0]
	v_pk_mul_f32 v[44:45], v[44:45], v[0:1] op_sel_hi:[1,0]
	v_pk_mul_f32 v[42:43], v[42:43], v[0:1] op_sel_hi:[1,0]
	v_pk_mul_f32 v[54:55], v[16:17], v[52:53] op_sel_hi:[1,0]
	v_pk_mul_f32 v[56:57], v[14:15], v[52:53] op_sel_hi:[1,0]
	v_pk_mul_f32 v[48:49], v[48:49], v[0:1] op_sel_hi:[1,0]
	v_pk_mul_f32 v[46:47], v[46:47], v[0:1] op_sel_hi:[1,0]
	v_pk_mul_f32 v[20:21], v[20:21], v[0:1] op_sel_hi:[1,0]
	v_pk_mul_f32 v[18:19], v[18:19], v[0:1] op_sel_hi:[1,0]
	v_pk_mul_f32 v[10:11], v[10:11], v[52:53] op_sel_hi:[1,0]
	v_pk_mul_f32 v[12:13], v[12:13], v[52:53] op_sel_hi:[1,0]
	v_pk_mul_f32 v[6:7], v[6:7], v[52:53] op_sel_hi:[1,0]
	v_pk_mul_f32 v[8:9], v[8:9], v[52:53] op_sel_hi:[1,0]
	v_pk_mul_f32 v[2:3], v[2:3], v[52:53] op_sel_hi:[1,0]
	v_pk_mul_f32 v[4:5], v[4:5], v[52:53] op_sel_hi:[1,0]
	v_lshlrev_b32_e32 v0, 1, v120
	s_and_b64 vcc, exec, s[0:1]
	s_waitcnt vmcnt(7)
	v_lshlrev_b32_e32 v14, 16, v206
	v_and_b32_e32 v15, 0xffff0000, v206
	v_lshlrev_b32_e32 v16, 16, v207
	v_and_b32_e32 v17, 0xffff0000, v207
	s_waitcnt vmcnt(6)
	v_lshlrev_b32_e32 v24, 16, v208
	v_and_b32_e32 v25, 0xffff0000, v208
	v_lshlrev_b32_e32 v26, 16, v209
	v_and_b32_e32 v27, 0xffff0000, v209
	s_waitcnt vmcnt(5)
	v_lshlrev_b32_e32 v58, 16, v210
	v_and_b32_e32 v59, 0xffff0000, v210
	v_lshlrev_b32_e32 v28, 16, v211
	v_and_b32_e32 v29, 0xffff0000, v211
	s_waitcnt vmcnt(4)
	v_lshlrev_b32_e32 v60, 16, v212
	v_and_b32_e32 v61, 0xffff0000, v212
	v_lshlrev_b32_e32 v30, 16, v213
	v_and_b32_e32 v31, 0xffff0000, v213
	v_pk_mul_f32 v[14:15], v[38:39], v[14:15]
	v_pk_mul_f32 v[16:17], v[40:41], v[16:17]
	v_pk_mul_f32 v[24:25], v[42:43], v[24:25]
	v_pk_mul_f32 v[26:27], v[44:45], v[26:27]
	v_pk_mul_f32 v[38:39], v[46:47], v[58:59]
	v_pk_mul_f32 v[28:29], v[48:49], v[28:29]
	v_pk_mul_f32 v[40:41], v[18:19], v[60:61]
	v_pk_mul_f32 v[30:31], v[20:21], v[30:31]
	v_cvt_pk_bf16_f32 v14, v14, v15
	v_cvt_pk_bf16_f32 v15, v16, v17
	v_cvt_pk_bf16_f32 v16, v24, v25
	v_cvt_pk_bf16_f32 v17, v26, v27
	v_cvt_pk_bf16_f32 v18, v38, v39
	v_cvt_pk_bf16_f32 v19, v28, v29
	v_cvt_pk_bf16_f32 v20, v40, v41
	v_cvt_pk_bf16_f32 v21, v30, v31
	v_permlane16_swap_b32_e32 v14, v16
	v_permlane16_swap_b32_e32 v15, v17
	s_waitcnt vmcnt(3)
	v_lshlrev_b32_e32 v24, 16, v218
	v_and_b32_e32 v25, 0xffff0000, v218
	v_permlane16_swap_b32_e32 v18, v20
	v_permlane16_swap_b32_e32 v19, v21
	global_store_dwordx4 v[22:23], v[14:17], off
	global_store_dwordx4 v[22:23], v[18:21], off offset:64
	s_nop 0
	v_lshlrev_b32_e32 v16, 16, v219
	v_and_b32_e32 v17, 0xffff0000, v219
	v_pk_mul_f32 v[14:15], v[56:57], v[24:25]
	v_pk_mul_f32 v[16:17], v[54:55], v[16:17]
	v_cvt_pk_bf16_f32 v14, v14, v15
	v_cvt_pk_bf16_f32 v15, v16, v17
	s_waitcnt vmcnt(4)
	v_lshlrev_b32_e32 v16, 16, v220
	v_and_b32_e32 v17, 0xffff0000, v220
	v_pk_mul_f32 v[10:11], v[10:11], v[16:17]
	s_nop 0
	v_cvt_pk_bf16_f32 v16, v10, v11
	v_lshlrev_b32_e32 v10, 16, v221
	v_and_b32_e32 v11, 0xffff0000, v221
	v_pk_mul_f32 v[10:11], v[12:13], v[10:11]
	v_permlane16_swap_b32_e32 v14, v16
	v_cvt_pk_bf16_f32 v17, v10, v11
	s_waitcnt vmcnt(3)
	v_lshlrev_b32_e32 v10, 16, v222
	v_and_b32_e32 v11, 0xffff0000, v222
	v_pk_mul_f32 v[6:7], v[6:7], v[10:11]
	v_lshlrev_b32_e32 v10, 16, v223
	v_and_b32_e32 v11, 0xffff0000, v223
	v_pk_mul_f32 v[8:9], v[8:9], v[10:11]
	v_cvt_pk_bf16_f32 v6, v6, v7
	v_cvt_pk_bf16_f32 v7, v8, v9
	s_waitcnt vmcnt(2)
	v_lshlrev_b32_e32 v8, 16, v224
	v_and_b32_e32 v9, 0xffff0000, v224
	v_pk_mul_f32 v[2:3], v[2:3], v[8:9]
	v_permlane16_swap_b32_e32 v15, v17
	v_cvt_pk_bf16_f32 v8, v2, v3
	v_lshlrev_b32_e32 v2, 16, v225
	v_and_b32_e32 v3, 0xffff0000, v225
	v_pk_mul_f32 v[2:3], v[4:5], v[2:3]
	v_permlane16_swap_b32_e32 v6, v8
	v_cvt_pk_bf16_f32 v9, v2, v3
	v_lshl_add_u64 v[2:3], v[118:119], 0, v[0:1]
	s_nop 0
	v_permlane16_swap_b32_e32 v7, v9
	global_store_dwordx4 v[2:3], v[14:17], off
	global_store_dwordx4 v[2:3], v[6:9], off offset:64
	s_cbranch_vccnz .LBB0_1429
; DEVI void attn_item(const P& p, int item, char* smem) {
;     ...
;         bf16x8 Qf[2][2];
; #pragma unroll
;         for (int m = 0; m < 2; ++m)
; #pragma unroll
;             for (int kk = 0; kk < 2; ++kk) Qf[m][kk] = *(const bf16x8*)(Q + (size_t)(mo + 16 * m + fr) * 1024 + kk * 32 + fq * 8);
;         f32x4 O[4][2];
; #pragma unroll
;         for (int nd = 0; nd < 4; ++nd)
; #pragma unroll
;             for (int m = 0; m < 2; ++m) O[nd][m] = (f32x4){0.f, 0.f, 0.f, 0.f};
;         float mrow[2], lrow[2];
; #pragma unroll
;         for (int m = 0; m < 2; ++m) { mrow[m] = sinkv; lrow[m] = (fq == 0) ? 1.0f : 0.0f; }
;     ...
;                 const size_t off = (size_t)(mo + 16 * m + fr) * 1024 + 16 * nd + 4 * fq;
;                 const uint2 g = *(const uint2*)(SGT + off);
.LBB0_1432:
	v_or_b32_e32 v0, s4, v174
	v_lshlrev_b32_e32 v122, 10, v0
	v_lshlrev_b32_e32 v0, 11, v0
	v_or_b32_e32 v120, 0x4000, v122
	v_lshl_add_u64 v[2:3], v[108:109], 0, v[0:1]
	v_lshlrev_b32_e32 v0, 1, v120
	global_load_dwordx4 v[22:25], v[2:3], off
	global_load_dwordx4 v[26:29], v[2:3], off offset:64
	v_lshl_add_u64 v[2:3], v[108:109], 0, v[0:1]
	global_load_dwordx4 v[30:33], v[2:3], off
	global_load_dwordx4 v[34:37], v[2:3], off offset:64
	v_or_b32_e32 v214, v122, v125
	v_lshlrev_b32_e32 v214, 1, v214
	v_mov_b32_e32 v215, 0
	v_lshl_add_u64 v[226:227], v[110:111], 0, v[214:215]
	global_load_dwordx2 v[206:207], v[226:227], off
	global_load_dwordx2 v[208:209], v[226:227], off offset:32
	global_load_dwordx2 v[210:211], v[226:227], off offset:64
	global_load_dwordx2 v[212:213], v[226:227], off offset:96
	v_or_b32_e32 v214, v120, v125
	v_lshlrev_b32_e32 v214, 1, v214
	v_lshl_add_u64 v[226:227], v[110:111], 0, v[214:215]
	global_load_dwordx2 v[218:219], v[226:227], off
	global_load_dwordx2 v[220:221], v[226:227], off offset:32
	global_load_dwordx2 v[222:223], v[226:227], off offset:64
	global_load_dwordx2 v[224:225], v[226:227], off offset:96
	v_mov_b32_e32 v2, v1
	v_mov_b32_e32 v3, v1
	v_mov_b32_e32 v0, v1
	v_mov_b64_e32 v[40:41], v[2:3]
	v_mov_b64_e32 v[16:17], v[2:3]
	v_mov_b64_e32 v[44:45], v[2:3]
	v_mov_b64_e32 v[12:13], v[2:3]
	v_mov_b64_e32 v[48:49], v[2:3]
	v_mov_b64_e32 v[8:9], v[2:3]
	v_mov_b64_e32 v[20:21], v[2:3]
	v_add_u32_e32 v140, s4, v137
	v_mov_b64_e32 v[38:39], v[0:1]
	v_mov_b64_e32 v[14:15], v[0:1]
	v_mov_b64_e32 v[42:43], v[0:1]
	v_mov_b64_e32 v[10:11], v[0:1]
	v_mov_b64_e32 v[46:47], v[0:1]
	v_mov_b64_e32 v[6:7], v[0:1]
	v_mov_b64_e32 v[18:19], v[0:1]
	v_mov_b64_e32 v[4:5], v[2:3]
	s_xor_b64 s[0:1], s[2:3], -1
	v_add_u32_e32 v141, 16, v140
	v_add_u32_e32 v142, -2, v140
	v_add_u32_e32 v143, -3, v140
	v_add_u32_e32 v144, -16, v140
	v_subrev_u32_e32 v145, 17, v140
	v_subrev_u32_e32 v146, 18, v140
	v_subrev_u32_e32 v147, 19, v140
	v_subrev_u32_e32 v148, 32, v140
	v_subrev_u32_e32 v149, 33, v140
	v_subrev_u32_e32 v150, 34, v140
	v_subrev_u32_e32 v151, 35, v140
	v_subrev_u32_e32 v152, 48, v140
	v_subrev_u32_e32 v153, 49, v140
	v_subrev_u32_e32 v154, 50, v140
	v_subrev_u32_e32 v155, 51, v140
	v_add_u32_e32 v156, 14, v140
	v_add_u32_e32 v157, 13, v140
	s_mov_b32 s28, 0
	s_mov_b32 s99, 0
	s_mov_b32 s47, s43
	v_mov_b32_e32 v158, v121
	v_mov_b32_e32 v139, v121
	v_mov_b32_e32 v160, v138
	v_mov_b32_e32 v159, v138
	v_mov_b64_e32 v[2:3], v[0:1]
	s_branch .LBB0_1435
